# diff attention loop: K/V prefetch addresses kept as two per-lane bases stepped one tile per half-step (3 VALU instead of 8 VALU+3 nop); no-op canonicalizing v_max removed from row-max chain
# speedup vs baseline: 1.0075x; 1.0041x over previous
; __global__ void __launch_bounds__(512, 2) fwd_megakernel(Args args) {
;     ...
;         case K_ATTN: {
;             char* albs = (char*)lds_raw;
;             const bool need_ctx = (layer != 3);
;             const int gx = (G % 8 == 0) ? G / 8 : G, xcd = (G % 8 == 0) ? bx % 8 : 0, vl = (G % 8 == 0) ? bx / 8 : bx, nxc = (G % 8 == 0) ? 8 : 1;
;             if (mixer == 0) {
;                 const float C = 0.125f * 1.4426950408889634f, thr = 8.f / 0.125f;
;                 const float* lv = AIN(11) + mj * 256; const float* sg = AIN(12) + mj * 128;
;                 const float linit = (layer == 0) ? LAMINIT0 : LAMINIT3;
;                 const float sa = wave_sum(lv[lane] * lv[64 + lane]), sb = wave_sum(lv[128 + lane] * lv[192 + lane]);
;                 const float lam = __expf(sa) - __expf(sb) + linit;
;                 const int per_x = 1024 / nxc, nlat = (per_x - vl + gx - 1) / gx, nctx = need_ctx ? (64 - bx + G - 1) / G : 0;
;                 bf16x8 pfv0 = {}, pfv1 = {}, pfk0 = {}; const int nunits = 2 * (nlat + (nctx > 0 ? nctx : 0));
;                 for (int i2 = 0; i2 < nunits; ++i2) {
;                     const int i = i2 >> 1, comp = i2 & 1;
;                     int b, h, seq; size_t qrow;
;                     if (i < nlat) { const int U = xcd * per_x + vl + i * gx, bh = U >> 4; b = bh >> 3; h = bh & 7; qrow = (size_t)b * RPB + CTXL + (U & 15) * 256; seq = RPB; }
;                     else { const int bh = bx + (i - nlat) * G; b = bh >> 3; h = bh & 7; qrow = (size_t)b * RPB; seq = CTXL; }
;                     const size_t krow = (size_t)b * RPB;
;                     int nbh = -1;
;                     if (comp == 0) nbh = b * 8 + h;
;                     else if (i2 + 1 < nunits) { const int i1 = i + 1; nbh = (i1 < nlat) ? ((xcd * per_x + vl + i1 * gx) >> 4) : bx + (i1 - nlat) * G; }
.LBB0_132:
	v_writelane_b32 v254, s44, 58
	s_cmp_gt_i32 s28, 3
	s_mov_b64 s[0:1], -1
	v_writelane_b32 v254, s45, 59
	v_writelane_b32 v254, s46, 60
	v_writelane_b32 v254, s47, 61
	v_writelane_b32 v254, s48, 62
	v_writelane_b32 v255, s50, 0
	v_writelane_b32 v254, s49, 63
	v_writelane_b32 v255, s51, 1
	s_movk_i32 s44, 0x1800
	s_mov_b32 s45, 0x4138aa3b
	s_mov_b64 s[42:43], 0x60000
	s_mov_b64 s[46:47], 0x60000
	s_cbranch_scc0 .LBB0_250
	s_ashr_i32 s2, s92, 31
	s_lshr_b32 s2, s2, 29
	s_add_i32 s2, s92, s2
	s_ashr_i32 s3, s2, 3
	s_and_b32 s2, s2, -8
	s_and_b32 s0, s93, 7
	s_ashr_i32 s1, s93, 3
	s_sub_i32 s2, s92, s2
	s_cmp_eq_u32 s0, 0
	s_waitcnt vmcnt(0)
	v_cndmask_b32_e64 v0, 0, 1, s[56:57]
	s_cselect_b32 s26, s1, s93
	s_cselect_b32 s18, s2, 0
	s_cselect_b32 s20, 3, 0
	s_cselect_b32 s19, s3, s92
	s_cmp_lg_u32 s30, 0
	v_cmp_ne_u32_e64 s[6:7], 1, v0
	s_cbranch_scc0 .LBB0_190
	s_and_b64 vcc, exec, s[6:7]
	s_mov_b32 s0, 0
	s_cbranch_vccnz .LBB0_136
	s_abs_i32 s0, s93
	v_cvt_f32_u32_e32 v0, s0
	s_sub_i32 s1, s93, s92
	s_add_i32 s2, s1, 63
	s_sub_i32 s1, 0xffffffc1, s1
	v_rcp_iflag_f32_e32 v0, v0
	s_xor_b32 s4, s2, s93
	s_sub_i32 s3, 0, s0
	s_max_i32 s1, s2, s1
	v_mul_f32_e32 v0, 0x4f7ffffe, v0
	v_cvt_u32_f32_e32 v0, v0
	s_ashr_i32 s2, s4, 31
	v_readfirstlane_b32 s4, v0
	s_mul_i32 s3, s3, s4
	s_mul_hi_u32 s3, s4, s3
	s_add_i32 s4, s4, s3
	s_mul_hi_u32 s3, s1, s4
	s_mul_i32 s4, s3, s0
	s_sub_i32 s1, s1, s4
	s_add_i32 s5, s3, 1
	s_sub_i32 s4, s1, s0
	s_cmp_ge_u32 s1, s0
	s_cselect_b32 s3, s5, s3
	s_cselect_b32 s1, s4, s1
	s_add_i32 s4, s3, 1
	s_cmp_ge_u32 s1, s0
	s_cselect_b32 s0, s4, s3
	s_xor_b32 s0, s0, s2
	s_sub_i32 s0, s0, s2
	s_max_i32 s0, s0, 0

; __device__ __forceinline__ void partialSM_pre(f32x16& p0, f32x16& p1, float& m_ref, float& alpha, const float thr2) {
;     ...
;   float pmax = p0[0];
; #pragma unroll
;   for (int r = 1; r < 16; ++r) pmax = fmaxf(pmax, p0[r]);
; #pragma unroll
;   for (int r = 0; r < 16; ++r) pmax = fmaxf(pmax, p1[r]);
;   { auto rr = __builtin_amdgcn_permlane32_swap(__float_as_uint(pmax), __float_as_uint(pmax), false, false);
;     pmax = fmaxf(__uint_as_float(rr[0]), __uint_as_float(rr[1])); }
;   if (__builtin_expect(__all(pmax <= thr2), 1)) { alpha = 1.f; }
.LBB0_147:
	v_max_f32_e32 v180, v96, v97
	v_max3_f32 v180, v180, v98, v99
	v_max3_f32 v180, v180, v100, v101
	v_max3_f32 v180, v180, v102, v103
	v_max3_f32 v180, v180, v104, v105
	v_max3_f32 v180, v180, v106, v107
	v_max3_f32 v180, v180, v108, v109
	v_max3_f32 v180, v180, v110, v111
	v_max3_f32 v180, v180, v80, v81
	v_max3_f32 v180, v180, v82, v83
	v_max3_f32 v180, v180, v84, v85
	v_max3_f32 v180, v180, v86, v87
	v_max3_f32 v180, v180, v88, v89
	v_max3_f32 v180, v180, v90, v91
	v_max3_f32 v180, v180, v92, v93
	v_max3_f32 v180, v180, v94, v95
	v_mov_b32_e32 v182, v180
	s_nop 1
	v_permlane32_swap_b32_e32 v180, v182
	v_max_f32_e32 v180, v180, v182
	s_waitcnt lgkmcnt(4)
	v_mfma_f32_32x32x16_bf16 v[0:15], v[64:67], v[210:213], v[0:15]
	ds_read_b64_tr_b16 v[210:211], v194 offset:0x200
	ds_read_b64_tr_b16 v[212:213], v194 offset:0xa00
	v_mfma_f32_32x32x16_bf16 v[0:15], v[68:71], v[214:217], v[0:15]
	ds_read_b64_tr_b16 v[214:215], v194 offset:0x1200
	ds_read_b64_tr_b16 v[216:217], v194 offset:0x1a00
	s_waitcnt lgkmcnt(4)
	v_mfma_f32_32x32x16_bf16 v[0:15], v[72:75], v[218:221], v[0:15]
	ds_read_b64_tr_b16 v[218:219], v194 offset:0x2200
	ds_read_b64_tr_b16 v[220:221], v194 offset:0x2a00
	v_mfma_f32_32x32x16_bf16 v[0:15], v[76:79], v[222:225], v[0:15]
	ds_read_b64_tr_b16 v[222:223], v194 offset:0x3200
	ds_read_b64_tr_b16 v[224:225], v194 offset:0x3a00
	s_waitcnt lgkmcnt(4)
	v_mfma_f32_32x32x16_bf16 v[48:63], v[64:67], v[210:213], v[48:63]
	ds_read_b64_tr_b16 v[210:211], v194 offset:0x400
	ds_read_b64_tr_b16 v[212:213], v194 offset:0xc00
	v_mfma_f32_32x32x16_bf16 v[48:63], v[68:71], v[214:217], v[48:63]
	ds_read_b64_tr_b16 v[214:215], v194 offset:0x1400
	ds_read_b64_tr_b16 v[216:217], v194 offset:0x1c00
	s_waitcnt lgkmcnt(4)
	v_mfma_f32_32x32x16_bf16 v[48:63], v[72:75], v[218:221], v[48:63]
	ds_read_b64_tr_b16 v[218:219], v194 offset:0x2400
	ds_read_b64_tr_b16 v[220:221], v194 offset:0x2c00
	v_mfma_f32_32x32x16_bf16 v[48:63], v[76:79], v[222:225], v[48:63]
	ds_read_b64_tr_b16 v[222:223], v194 offset:0x3400
	ds_read_b64_tr_b16 v[224:225], v194 offset:0x3c00
	s_waitcnt lgkmcnt(4)
	v_mfma_f32_32x32x16_bf16 v[32:47], v[64:67], v[210:213], v[32:47]
	ds_read_b64_tr_b16 v[210:211], v194 offset:0x600
	ds_read_b64_tr_b16 v[212:213], v194 offset:0xe00
	v_mfma_f32_32x32x16_bf16 v[32:47], v[68:71], v[214:217], v[32:47]
	ds_read_b64_tr_b16 v[214:215], v194 offset:0x1600
	ds_read_b64_tr_b16 v[216:217], v194 offset:0x1e00
	s_waitcnt lgkmcnt(4)
	v_mfma_f32_32x32x16_bf16 v[32:47], v[72:75], v[218:221], v[32:47]
	ds_read_b64_tr_b16 v[218:219], v194 offset:0x2600
	ds_read_b64_tr_b16 v[220:221], v194 offset:0x2e00
	v_mfma_f32_32x32x16_bf16 v[32:47], v[76:79], v[222:225], v[32:47]
	ds_read_b64_tr_b16 v[222:223], v194 offset:0x3600
	ds_read_b64_tr_b16 v[224:225], v194 offset:0x3e00
	s_waitcnt lgkmcnt(4)
	v_mfma_f32_32x32x16_bf16 v[16:31], v[64:67], v[210:213], v[16:31]
	v_mfma_f32_32x32x16_bf16 v[16:31], v[68:71], v[214:217], v[16:31]
	s_waitcnt lgkmcnt(0)
	v_mfma_f32_32x32x16_bf16 v[16:31], v[72:75], v[218:221], v[16:31]
	s_waitcnt vmcnt(4)
	ds_write_b128 v195, v[150:153] offset:32768
	ds_write_b128 v196, v[146:149] offset:32768
	v_mfma_f32_32x32x16_bf16 v[16:31], v[76:79], v[222:225], v[16:31]
	v_cmp_ge_f32_e32 vcc, s45, v180
	s_cmp_eq_u64 vcc, exec
	v_mov_b32_e32 v210, 1.0
	s_cbranch_scc0 .LBB0_164

; __device__ __forceinline__ void partialSM_pre(f32x16& p0, f32x16& p1, float& m_ref, float& alpha, const float thr2) {
;     ...
;   float pmax = p0[0];
; #pragma unroll
;   for (int r = 1; r < 16; ++r) pmax = fmaxf(pmax, p0[r]);
; #pragma unroll
;   for (int r = 0; r < 16; ++r) pmax = fmaxf(pmax, p1[r]);
;   { auto rr = __builtin_amdgcn_permlane32_swap(__float_as_uint(pmax), __float_as_uint(pmax), false, false);
;     pmax = fmaxf(__uint_as_float(rr[0]), __uint_as_float(rr[1])); }
;   if (__builtin_expect(__all(pmax <= thr2), 1)) { alpha = 1.f; }
.LBB0_156:
	v_max_f32_e32 v180, v96, v97
	v_max3_f32 v180, v180, v98, v99
	v_max3_f32 v180, v180, v100, v101
	v_max3_f32 v180, v180, v102, v103
	v_max3_f32 v180, v180, v104, v105
	v_max3_f32 v180, v180, v106, v107
	v_max3_f32 v180, v180, v108, v109
	v_max3_f32 v180, v180, v110, v111
	v_max3_f32 v180, v180, v64, v65
	v_max3_f32 v180, v180, v66, v67
	v_max3_f32 v180, v180, v68, v69
	v_max3_f32 v180, v180, v70, v71
	v_max3_f32 v180, v180, v72, v73
	v_max3_f32 v180, v180, v74, v75
	v_max3_f32 v180, v180, v76, v77
	v_max3_f32 v180, v180, v78, v79
	v_mov_b32_e32 v182, v180
	s_nop 1
	v_permlane32_swap_b32_e32 v180, v182
	v_max_f32_e32 v180, v180, v182
	s_waitcnt lgkmcnt(4)
	v_mfma_f32_32x32x16_bf16 v[0:15], v[80:83], v[214:217], v[0:15]
	ds_read_b64_tr_b16 v[214:215], v191 offset:0x200
	ds_read_b64_tr_b16 v[216:217], v191 offset:0xa00
	v_mfma_f32_32x32x16_bf16 v[0:15], v[84:87], v[218:221], v[0:15]
	ds_read_b64_tr_b16 v[218:219], v191 offset:0x1200
	ds_read_b64_tr_b16 v[220:221], v191 offset:0x1a00
	s_waitcnt lgkmcnt(4)
	v_mfma_f32_32x32x16_bf16 v[0:15], v[88:91], v[222:225], v[0:15]
	ds_read_b64_tr_b16 v[222:223], v191 offset:0x2200
	ds_read_b64_tr_b16 v[224:225], v191 offset:0x2a00
	v_mfma_f32_32x32x16_bf16 v[0:15], v[92:95], v[234:237], v[0:15]
	ds_read_b64_tr_b16 v[234:235], v191 offset:0x3200
	ds_read_b64_tr_b16 v[236:237], v191 offset:0x3a00
	s_waitcnt lgkmcnt(4)
	v_mfma_f32_32x32x16_bf16 v[48:63], v[80:83], v[214:217], v[48:63]
	ds_read_b64_tr_b16 v[214:215], v191 offset:0x400
	ds_read_b64_tr_b16 v[216:217], v191 offset:0xc00
	v_mfma_f32_32x32x16_bf16 v[48:63], v[84:87], v[218:221], v[48:63]
	ds_read_b64_tr_b16 v[218:219], v191 offset:0x1400
	ds_read_b64_tr_b16 v[220:221], v191 offset:0x1c00
	s_waitcnt lgkmcnt(4)
	v_mfma_f32_32x32x16_bf16 v[48:63], v[88:91], v[222:225], v[48:63]
	ds_read_b64_tr_b16 v[222:223], v191 offset:0x2400
	ds_read_b64_tr_b16 v[224:225], v191 offset:0x2c00
	v_mfma_f32_32x32x16_bf16 v[48:63], v[92:95], v[234:237], v[48:63]
	ds_read_b64_tr_b16 v[234:235], v191 offset:0x3400
	ds_read_b64_tr_b16 v[236:237], v191 offset:0x3c00
	s_waitcnt lgkmcnt(4)
	v_mfma_f32_32x32x16_bf16 v[32:47], v[80:83], v[214:217], v[32:47]
	ds_read_b64_tr_b16 v[214:215], v191 offset:0x600
	ds_read_b64_tr_b16 v[216:217], v191 offset:0xe00
	v_mfma_f32_32x32x16_bf16 v[32:47], v[84:87], v[218:221], v[32:47]
	ds_read_b64_tr_b16 v[218:219], v191 offset:0x1600
	ds_read_b64_tr_b16 v[220:221], v191 offset:0x1e00
	s_waitcnt lgkmcnt(4)
	v_mfma_f32_32x32x16_bf16 v[32:47], v[88:91], v[222:225], v[32:47]
	ds_read_b64_tr_b16 v[222:223], v191 offset:0x2600
	ds_read_b64_tr_b16 v[224:225], v191 offset:0x2e00
	v_mfma_f32_32x32x16_bf16 v[32:47], v[92:95], v[234:237], v[32:47]
	ds_read_b64_tr_b16 v[234:235], v191 offset:0x3600
	ds_read_b64_tr_b16 v[236:237], v191 offset:0x3e00
	s_waitcnt lgkmcnt(4)
	v_mfma_f32_32x32x16_bf16 v[16:31], v[80:83], v[214:217], v[16:31]
	v_mfma_f32_32x32x16_bf16 v[16:31], v[84:87], v[218:221], v[16:31]
	s_waitcnt lgkmcnt(0)
	v_mfma_f32_32x32x16_bf16 v[16:31], v[88:91], v[222:225], v[16:31]
	s_waitcnt vmcnt(4)
	ds_write_b128 v195, v[170:173] offset:49152
	ds_write_b128 v196, v[174:177] offset:49152
	v_mfma_f32_32x32x16_bf16 v[16:31], v[92:95], v[234:237], v[16:31]
	v_cmp_ge_f32_e32 vcc, s45, v180
	s_cmp_eq_u64 vcc, exec
	v_mov_b32_e32 v170, 1.0
	s_cbranch_scc0 .LBB0_166

; #define SLOAD_A(k0) do { vs0a = *reinterpret_cast<const bf16x8*>(&Vh[(long)((k0) + sr) * LDK + sc]); vs1a = *reinterpret_cast<const bf16x8*>(&Vh[(long)((k0) + 32 + sr) * LDK + sc]); KLOAD(ks0a, ks1a, k0); } while (0)
; #define SLOAD_B(k0) do { vs0b = *reinterpret_cast<const bf16x8*>(&Vh[(long)((k0) + sr) * LDK + sc]); vs1b = *reinterpret_cast<const bf16x8*>(&Vh[(long)((k0) + 32 + sr) * LDK + sc]); KLOAD(ks0b, ks1b, k0); } while (0)
; #define SWRITE_A(b) do { *(bf16x8*)(V_lds + (b) * SHM_V + vst0) = vs0a; *(bf16x8*)(V_lds + (b) * SHM_V + vst1) = vs1a; KWRITE(b, ks0a, ks1a); } while (0)
; #define SWRITE_B(b) do { *(bf16x8*)(V_lds + (b) * SHM_V + vst0) = vs0b; *(bf16x8*)(V_lds + (b) * SHM_V + vst1) = vs1b; KWRITE(b, ks0b, ks1b); } while (0)
; #define SWAIT() do { if constexpr (ND0 == 4) asm volatile("s_waitcnt vmcnt(3)" ::: "memory"); else asm volatile("s_waitcnt vmcnt(4)" ::: "memory"); } while (0)
; #define PSM(P0, P1, MN, AL) do { if constexpr (PRE) partialSM_pre(P0, P1, m_reg, AL, 11.541560327111707f); else partialSM(P0, P1, m_reg, MN, AL, C, thr_raw); } while (0)
; template <int ND0, int LDQ, int LDK, int LDO> ...
;     ...
;   f32x16 pA0, pA1, pB0, pB1; float mnA, mnB, alA, alB; bf16x8 pa0, pa1, pa2, pa3; const int NT = seq / KVBLK;
;   const char* Kq0 = K_lds + kofs; const char* Kq1 = K_lds + SHM_K + kofs;
;   if (ND0 == 4 && have_pf) { vs0a = pfv0; vs1a = pfv1; ks0a = pfk0; } else { SLOAD_A(0); }
;   asm volatile("s_waitcnt vmcnt(0)" ::: "memory"); SWRITE_A(0); __syncthreads();
;   qkt<ND0>(pA0, pA1, Kq0, qr, r32, hi); PSM(pA0, pA1, mnA, alA);
;   SLOAD_B(KVBLK); if (2 < NT) SLOAD_A(2 * KVBLK);
;   SWAIT(); SWRITE_B(1); __syncthreads();
;   for (int j = 1; j + 1 < NT; j += 2) {
.LBB0_213:
	v_add_u32_e32 v17, 64, v21
	v_mov_b64_e32 v[36:37], s[20:21]
	v_mad_i64_i32 v[24:25], s[20:21], v17, s44, v[36:37]
	v_add_u32_e32 v17, 0x60, v21
	v_mov_b32_e32 v161, v113
	v_mad_i64_i32 v[26:27], s[20:21], v17, s44, v[36:37]
	v_add_u32_e32 v17, 64, v22
	v_mov_b64_e32 v[38:39], s[18:19]
	v_add_u32_e32 v23, 0x80, v22
	v_lshl_add_u64 v[24:25], v[24:25], 0, v[160:161]
	v_lshl_add_u64 v[28:29], v[26:27], 0, v[160:161]
	v_mov_b32_e32 v19, v113
	v_mad_i64_i32 v[32:33], s[18:19], v17, s44, v[38:39]
	v_add_u32_e32 v40, 0xa0, v21
	v_add_u32_e32 v42, 0x80, v21
	v_mad_i64_i32 v[38:39], s[18:19], v23, s44, v[38:39]
	global_load_dwordx4 v[24:27], v[24:25], off
	s_nop 0
	global_load_dwordx4 v[28:31], v[28:29], off
	v_lshl_add_u64 v[32:33], v[32:33], 0, v[18:19]
	v_mad_i64_i32 v[40:41], s[18:19], v40, s44, v[36:37]
	v_mad_i64_i32 v[36:37], s[18:19], v42, s44, v[36:37]
	v_lshl_add_u64 v[38:39], v[38:39], 0, v[18:19]
	global_load_dwordx4 v[32:35], v[32:33], off offset:2048
	v_lshl_add_u64 v[40:41], v[40:41], 0, v[160:161]
	v_lshl_add_u64 v[36:37], v[36:37], 0, v[160:161]
	global_load_dwordx4 v[138:141], v[38:39], off offset:2048
	global_load_dwordx4 v[134:137], v[40:41], off
	global_load_dwordx4 v[130:133], v[36:37], off
	v_and_b32_e32 v185, 63, v20
	s_lshl_b32 s38, s38, 7
	s_add_i32 s20, 0, 0x10000
	v_exp_f32_e32 v177, v3
	v_lshlrev_b32_e32 v3, 4, v185
	v_exp_f32_e32 v174, v2
	v_exp_f32_e32 v152, v4
	v_mad_i64_i32 v[166:167], s[18:19], v22, s44, 0
	v_lshlrev_b32_e32 v2, 3, v185
	v_lshlrev_b32_e32 v4, 1, v185
	s_cmp_lg_u32 0, -1
	v_and_b32_e32 v3, 0xc0, v3
	v_exp_f32_e32 v175, v5
	v_and_b32_e32 v4, 32, v4
	v_and_b32_e32 v5, 0x100, v2
	s_cselect_b32 s18, 0, 0
	v_and_or_b32 v2, v2, 24, v3
	v_cndmask_b32_e64 v19, 0, 1, s[2:3]
	v_exp_f32_e32 v176, v0
	v_exp_f32_e32 v206, v1
	v_mov_b64_e32 v[0:1], s[6:7]
	s_add_i32 s19, s18, 0x4000
	v_or3_b32 v2, v2, v4, v5
	v_readlane_b32 s48, v254, 14
	v_add_u32_e32 v192, s18, v2
	v_add_u32_e32 v190, s19, v2
	v_mad_i64_i32 v[2:3], s[18:19], v22, s44, v[0:1]
	v_lshl_or_b32 v4, v19, 7, v16
	v_mov_b32_e32 v5, v113
	v_readlane_b32 s50, v254, 16
	v_readlane_b32 s51, v254, 17
	v_lshl_add_u64 v[2:3], v[2:3], 0, v[4:5]
	s_mov_b64 s[42:43], s[50:51]
	v_lshl_add_u64 v[170:171], s[42:43], 0, v[2:3]
	v_and_b32_e32 v2, 15, v20
	v_exp_f32_e32 v151, v6
	v_exp_f32_e32 v153, v7
	v_exp_f32_e32 v147, v8
	v_exp_f32_e32 v149, v9
	v_exp_f32_e32 v145, v10
	v_exp_f32_e32 v148, v11
	v_exp_f32_e32 v143, v12
	v_exp_f32_e32 v146, v13
	v_exp_f32_e32 v142, v14
	v_exp_f32_e32 v144, v15
	v_mad_i64_i32 v[0:1], s[18:19], v21, s44, v[0:1]
	v_lshlrev_b32_e32 v2, 4, v2
	v_mov_b32_e32 v3, v113
	v_and_b32_e32 v17, 0x3fffffc0, v20
	s_waitcnt vmcnt(3)
	v_lshl_add_u64 v[0:1], v[0:1], 0, v[2:3]
	v_mov_b32_e32 v14, v113
	v_mov_b32_e32 v15, v113
	v_lshrrev_b32_e32 v188, 1, v18
	v_lshl_add_u32 v161, v17, 2, s20
	s_waitcnt vmcnt(5)
	ds_write_b128 v193, v[24:27] offset:16384
	s_waitcnt vmcnt(4)
	ds_write_b128 v194, v[28:31] offset:16384
	s_waitcnt vmcnt(3)
	ds_write_b128 v195, v[32:35] offset:49152
	v_mad_i64_i32 v[168:169], s[18:19], v21, s44, 0
	v_lshl_add_u64 v[172:173], s[42:43], 0, v[0:1]
	v_mov_b32_e32 v0, v113
	v_mov_b32_e32 v1, v113
	v_mov_b32_e32 v2, v113
	v_mov_b32_e32 v4, v113
	v_mov_b32_e32 v6, v113
	v_mov_b32_e32 v7, v113
	v_mov_b32_e32 v8, v113
	v_mov_b32_e32 v9, v113
	v_mov_b32_e32 v10, v113
	v_mov_b32_e32 v11, v113
	v_mov_b32_e32 v12, v113
	v_mov_b32_e32 v13, v113
	v_mov_b64_e32 v[62:63], v[14:15]
	v_mov_b64_e32 v[46:47], v[14:15]
	v_mov_b64_e32 v[30:31], v[14:15]
	s_mov_b32 s40, 4
	v_cmp_gt_u32_e64 s[6:7], 32, v185
	v_lshl_add_u32 v187, v157, 2, v161
	v_mov_b32_e32 v189, 0
	v_mov_b64_e32 v[60:61], v[12:13]
	v_mov_b64_e32 v[58:59], v[10:11]
	v_mov_b64_e32 v[56:57], v[8:9]
	v_mov_b64_e32 v[54:55], v[6:7]
	v_mov_b64_e32 v[52:53], v[4:5]
	v_mov_b64_e32 v[50:51], v[2:3]
	v_mov_b64_e32 v[48:49], v[0:1]
	v_mov_b64_e32 v[44:45], v[12:13]
	v_mov_b64_e32 v[42:43], v[10:11]
	v_mov_b64_e32 v[40:41], v[8:9]
	v_mov_b64_e32 v[38:39], v[6:7]
	v_mov_b64_e32 v[36:37], v[4:5]
	v_mov_b64_e32 v[34:35], v[2:3]
	v_mov_b64_e32 v[32:33], v[0:1]
	v_mov_b64_e32 v[28:29], v[12:13]
	v_mov_b64_e32 v[26:27], v[10:11]
	v_mov_b64_e32 v[24:25], v[8:9]
	v_mov_b64_e32 v[22:23], v[6:7]
	v_mov_b64_e32 v[20:21], v[4:5]
	v_mov_b64_e32 v[18:19], v[2:3]
	v_mov_b64_e32 v[16:17], v[0:1]
	s_waitcnt lgkmcnt(0)
	s_barrier
	v_readlane_b32 s49, v254, 15
	s_add_u32 s98, s34, 0x13221000
	s_addc_u32 s99, s35, 0
	v_lshl_add_u64 v[172:173], v[172:173], 0, s[98:99]
	s_add_u32 s98, s34, 0x13220000
	s_addc_u32 s99, s35, 0
	v_lshl_add_u64 v[170:171], v[170:171], 0, s[98:99]
	s_mov_b32 s34, 0x30000
	ds_read_b128 v[80:83], v197 offset:49152
	ds_read_b128 v[84:87], v197 offset:57344
; #define SBAR() __builtin_amdgcn_sched_barrier(0)
; #define KWRITE(b, src0, src1) do { if constexpr (ND0 == 4) { *(bf16x8*)(K_lds + (b) * SHM_K + KSWZ(kr, kcb)) = src0; } \
;     else { int kc = sc * 2; *(bf16x8*)(K_lds + (b) * SHM_K + KSWZ(sr, kc)) = src0; *(bf16x8*)(K_lds + (b) * SHM_K + KSWZ(32 + sr, kc)) = src1; } } while (0)
; #define SLOAD_B(k0) do { vs0b = *reinterpret_cast<const bf16x8*>(&Vh[(long)((k0) + sr) * LDK + sc]); vs1b = *reinterpret_cast<const bf16x8*>(&Vh[(long)((k0) + 32 + sr) * LDK + sc]); KLOAD(ks0b, ks1b, k0); } while (0)
; #define PSM(P0, P1, MN, AL) do { if constexpr (PRE) partialSM_pre(P0, P1, m_reg, AL, 11.541560327111707f); else partialSM(P0, P1, m_reg, MN, AL, C, thr_raw); } while (0)
; __device__ __forceinline__ void finishSM(f32x16& p0, f32x16& p1, float alpha, float& l_reg, bf16x8& pa0, bf16x8& pa1, bf16x8& pa2, bf16x8& pa3) {
; #pragma unroll
;   for (int r = 0; r < 16; ++r) p1[r] = __builtin_amdgcn_exp2f(p1[r]);
;   float ps = 0;
; #pragma unroll
;   for (int r = 0; r < 16; ++r) ps += p0[r];
; #pragma unroll
;   for (int r = 0; r < 16; ++r) ps += p1[r];
;   { auto rr = __builtin_amdgcn_permlane32_swap(__float_as_uint(ps), __float_as_uint(ps), false, false);
;     ps = __uint_as_float(rr[0]) + __uint_as_float(rr[1]); }
;   l_reg = l_reg * alpha + ps;
;     ...
;   PK4(p0, 0, pa0); PK4(p0, 8, pa1); PK4(p1, 0, pa2); PK4(p1, 8, pa3);
;     ...
; }
; template <int ND0>
; __device__ __forceinline__ void qkt(f32x16& p0, f32x16& p1, const char* Ks, const bf16x8* qr, int r32, int hi) {
;   p0 = f32x16{}; p1 = f32x16{};
; #pragma unroll
;   for (int d0 = 0; d0 < ND0; ++d0) { int cb = (d0 * 16 + hi * 8) * 2;
;     bf16x8 b0 = *reinterpret_cast<const bf16x8*>(Ks + KSWZ(r32, cb));
;     bf16x8 b1 = *reinterpret_cast<const bf16x8*>(Ks + KSWZ(32 + r32, cb));
;     p0 = __builtin_amdgcn_mfma_f32_32x32x16_bf16(b0, qr[d0], p0, 0, 0, 0);
;     p1 = __builtin_amdgcn_mfma_f32_32x32x16_bf16(b1, qr[d0], p1, 0, 0, 0); }
; }
; template <int ND0, int LDQ, int LDK, int LDO> ...
;     ...
;   for (int j = 1; j + 1 < NT; j += 2) {
;     SBAR(); qkt<ND0>(pB0, pB1, Kq1, qr, r32, hi);
;     finishSM(pA0, pA1, alA, l_reg, pa0, pa1, pa2, pa3); SBAR();
;     SLOAD_B((j + 2) * KVBLK); SBAR();
;     pv_d0(o, vb0, pa0, pa1, pa2, pa3); KWRITE(0, ks0a, ks1a); PSM(pB0, pB1, mnB, alB);
.LBB0_214:
	ds_read_b128 v[202:205], v198 offset:49152
	ds_read_b128 v[208:211], v198 offset:57344
	ds_read_b128 v[222:225], v199 offset:49152
	ds_read_b128 v[234:237], v199 offset:57344
	ds_read_b128 v[238:241], v196 offset:49152
	ds_read_b128 v[244:247], v196 offset:57344
	v_exp_f32_e32 v150, v64
	v_add_f32_e32 v64, 0, v176
	s_waitcnt lgkmcnt(6)
	v_mfma_f32_32x32x16_bf16 v[96:111], v[80:83], v[126:129], 0
	v_add_f32_e32 v64, v206, v64
	v_add_f32_e32 v64, v174, v64
	v_add_f32_e32 v64, v177, v64
	v_add_f32_e32 v64, v152, v64
	v_add_f32_e32 v64, v175, v64
	v_add_f32_e32 v64, v151, v64
	v_add_f32_e32 v64, v153, v64
	v_mfma_f32_32x32x16_bf16 v[80:95], v[84:87], v[126:129], 0
	v_add_f32_e32 v64, v147, v64
	v_add_f32_e32 v64, v149, v64
	v_add_f32_e32 v64, v145, v64
	v_add_f32_e32 v64, v148, v64
	v_add_f32_e32 v64, v143, v64
	v_add_f32_e32 v64, v146, v64
	v_add_f32_e32 v64, v142, v64
	s_waitcnt lgkmcnt(4)
	v_mfma_f32_32x32x16_bf16 v[96:111], v[202:205], v[122:125], v[96:111]
	v_add_f32_e32 v64, v144, v64
	v_exp_f32_e32 v207, v68
	v_add_f32_e32 v64, v150, v64
	v_exp_f32_e32 v212, v73
	v_exp_f32_e32 v213, v74
	v_exp_f32_e32 v214, v75
	v_exp_f32_e32 v215, v76
	v_mfma_f32_32x32x16_bf16 v[80:95], v[208:211], v[122:125], v[80:95]
	v_exp_f32_e32 v216, v77
	v_exp_f32_e32 v217, v78
	v_exp_f32_e32 v79, v79
	s_waitcnt lgkmcnt(2)
	v_mfma_f32_32x32x16_bf16 v[96:111], v[222:225], v[118:121], v[96:111]
	v_mfma_f32_32x32x16_bf16 v[80:95], v[234:237], v[118:121], v[80:95]
	s_waitcnt lgkmcnt(0)
	v_mfma_f32_32x32x16_bf16 v[96:111], v[238:241], v[114:117], v[96:111]
	v_exp_f32_e32 v203, v65
	v_exp_f32_e32 v204, v66
	v_exp_f32_e32 v205, v67
	v_add_f32_e32 v64, v203, v64
	v_add_f32_e32 v64, v204, v64
	v_add_f32_e32 v64, v205, v64
	v_mfma_f32_32x32x16_bf16 v[80:95], v[244:247], v[114:117], v[80:95]
	v_exp_f32_e32 v208, v69
	v_exp_f32_e32 v209, v70
	v_exp_f32_e32 v210, v71
	v_exp_f32_e32 v211, v72
	v_add_f32_e32 v64, v207, v64
	v_add_f32_e32 v64, v208, v64
	v_add_f32_e32 v64, v209, v64
	v_add_f32_e32 v64, v210, v64
	v_add_f32_e32 v64, v211, v64
	v_add_f32_e32 v64, v212, v64
	v_add_f32_e32 v64, v213, v64
	v_add_f32_e32 v64, v214, v64
	v_add_f32_e32 v64, v215, v64
	v_add_f32_e32 v64, v216, v64
	v_add_f32_e32 v64, v217, v64
	v_add_f32_e32 v201, v79, v64
	v_mov_b32_e32 v202, v201
	v_cvt_pk_bf16_f32 v64, v176, v206
	v_cvt_pk_bf16_f32 v65, v174, v177
	v_cvt_pk_bf16_f32 v66, v152, v175
	v_cvt_pk_bf16_f32 v67, v151, v153
	v_cvt_pk_bf16_f32 v68, v147, v149
	v_cvt_pk_bf16_f32 v69, v145, v148
	v_cvt_pk_bf16_f32 v70, v143, v146
	v_cvt_pk_bf16_f32 v71, v142, v144
	v_cvt_pk_bf16_f32 v72, v150, v203
	v_cvt_pk_bf16_f32 v73, v204, v205
	v_cvt_pk_bf16_f32 v74, v207, v208
	v_cvt_pk_bf16_f32 v75, v209, v210
	v_cvt_pk_bf16_f32 v76, v211, v212
	v_cvt_pk_bf16_f32 v77, v213, v214
	v_cvt_pk_bf16_f32 v78, v215, v216
	v_cvt_pk_bf16_f32 v79, v217, v79
	v_permlane32_swap_b32_e32 v201, v202
	v_permlane32_swap_b32_e32 v64, v66
	v_permlane32_swap_b32_e32 v65, v67
	v_permlane32_swap_b32_e32 v68, v70
	v_permlane32_swap_b32_e32 v69, v71
	v_permlane32_swap_b32_e32 v72, v74
	v_permlane32_swap_b32_e32 v73, v75
	v_permlane32_swap_b32_e32 v76, v78
	v_permlane32_swap_b32_e32 v77, v79
	global_load_dwordx4 v[142:145], v[172:173], off
	v_lshl_add_u64 v[174:175], v[172:173], 0, s[34:35]
	global_load_dwordx4 v[146:149], v[174:175], off
	global_load_dwordx4 v[150:153], v[170:171], off offset:2048
	v_lshl_add_u64 v[172:173], v[172:173], 0, s[46:47]
	v_lshl_add_u64 v[170:171], v[170:171], 0, s[46:47]
	v_cmp_neq_f32_e32 vcc, 0, v191
	ds_read_b64_tr_b16 v[204:205], v192 offset:0
	ds_read_b64_tr_b16 v[206:207], v192 offset:0x800
	ds_read_b64_tr_b16 v[208:209], v192 offset:0x1000
	ds_read_b64_tr_b16 v[210:211], v192 offset:0x1800
	ds_read_b64_tr_b16 v[212:213], v192 offset:0x2000
	ds_read_b64_tr_b16 v[214:215], v192 offset:0x2800
	ds_read_b64_tr_b16 v[216:217], v192 offset:0x3000
	ds_read_b64_tr_b16 v[218:219], v192 offset:0x3800
	s_cbranch_vccnz .LBB0_230
; __device__ __forceinline__ void partialSM_pre(f32x16& p0, f32x16& p1, float& m_ref, float& alpha, const float thr2) {
;     ...
;   float pmax = p0[0];
; #pragma unroll
;   for (int r = 1; r < 16; ++r) pmax = fmaxf(pmax, p0[r]);
; #pragma unroll
;   for (int r = 0; r < 16; ++r) pmax = fmaxf(pmax, p1[r]);
;   { auto rr = __builtin_amdgcn_permlane32_swap(__float_as_uint(pmax), __float_as_uint(pmax), false, false);
;     pmax = fmaxf(__uint_as_float(rr[0]), __uint_as_float(rr[1])); }
;   if (__builtin_expect(__all(pmax <= thr2), 1)) { alpha = 1.f; }
.LBB0_215:
	v_max_f32_e32 v252, v96, v97
	v_max3_f32 v252, v252, v98, v99
	v_max3_f32 v252, v252, v100, v101
	v_max3_f32 v252, v252, v102, v103
	v_max3_f32 v252, v252, v104, v105
	v_max3_f32 v252, v252, v106, v107
	v_max3_f32 v252, v252, v108, v109
	v_max3_f32 v252, v252, v110, v111
	v_max3_f32 v252, v252, v80, v81
	v_max3_f32 v252, v252, v82, v83
	v_max3_f32 v252, v252, v84, v85
	v_max3_f32 v252, v252, v86, v87
	v_max3_f32 v252, v252, v88, v89
	v_max3_f32 v252, v252, v90, v91
	v_max3_f32 v252, v252, v92, v93
	v_max3_f32 v252, v252, v94, v95
	v_mov_b32_e32 v253, v252
	s_nop 1
	v_permlane32_swap_b32_e32 v252, v253
	v_max_f32_e32 v252, v252, v253
	s_waitcnt lgkmcnt(4)
	v_mfma_f32_32x32x16_bf16 v[0:15], v[64:67], v[204:207], v[0:15]
	ds_read_b64_tr_b16 v[204:205], v192 offset:0x200
	ds_read_b64_tr_b16 v[206:207], v192 offset:0xa00
	v_mfma_f32_32x32x16_bf16 v[0:15], v[68:71], v[208:211], v[0:15]
	ds_read_b64_tr_b16 v[208:209], v192 offset:0x1200
	ds_read_b64_tr_b16 v[210:211], v192 offset:0x1a00
	s_waitcnt lgkmcnt(4)
	v_mfma_f32_32x32x16_bf16 v[0:15], v[72:75], v[212:215], v[0:15]
	ds_read_b64_tr_b16 v[212:213], v192 offset:0x2200
	ds_read_b64_tr_b16 v[214:215], v192 offset:0x2a00
	v_mfma_f32_32x32x16_bf16 v[0:15], v[76:79], v[216:219], v[0:15]
	ds_read_b64_tr_b16 v[216:217], v192 offset:0x3200
	ds_read_b64_tr_b16 v[218:219], v192 offset:0x3a00
	s_waitcnt lgkmcnt(4)
	v_mfma_f32_32x32x16_bf16 v[48:63], v[64:67], v[204:207], v[48:63]
	ds_read_b64_tr_b16 v[204:205], v192 offset:0x400
	ds_read_b64_tr_b16 v[206:207], v192 offset:0xc00
	v_mfma_f32_32x32x16_bf16 v[48:63], v[68:71], v[208:211], v[48:63]
	ds_read_b64_tr_b16 v[208:209], v192 offset:0x1400
	ds_read_b64_tr_b16 v[210:211], v192 offset:0x1c00
	s_waitcnt lgkmcnt(4)
	v_mfma_f32_32x32x16_bf16 v[48:63], v[72:75], v[212:215], v[48:63]
	ds_read_b64_tr_b16 v[212:213], v192 offset:0x2400
	ds_read_b64_tr_b16 v[214:215], v192 offset:0x2c00
	v_mfma_f32_32x32x16_bf16 v[48:63], v[76:79], v[216:219], v[48:63]
	ds_read_b64_tr_b16 v[216:217], v192 offset:0x3400
	ds_read_b64_tr_b16 v[218:219], v192 offset:0x3c00
	s_waitcnt lgkmcnt(4)
	v_mfma_f32_32x32x16_bf16 v[32:47], v[64:67], v[204:207], v[32:47]
	ds_read_b64_tr_b16 v[204:205], v192 offset:0x600
	ds_read_b64_tr_b16 v[206:207], v192 offset:0xe00
	v_mfma_f32_32x32x16_bf16 v[32:47], v[68:71], v[208:211], v[32:47]
	ds_read_b64_tr_b16 v[208:209], v192 offset:0x1600
	ds_read_b64_tr_b16 v[210:211], v192 offset:0x1e00
	s_waitcnt lgkmcnt(4)
	v_mfma_f32_32x32x16_bf16 v[32:47], v[72:75], v[212:215], v[32:47]
	ds_read_b64_tr_b16 v[212:213], v192 offset:0x2600
	ds_read_b64_tr_b16 v[214:215], v192 offset:0x2e00
	v_mfma_f32_32x32x16_bf16 v[32:47], v[76:79], v[216:219], v[32:47]
	ds_read_b64_tr_b16 v[216:217], v192 offset:0x3600
	ds_read_b64_tr_b16 v[218:219], v192 offset:0x3e00
	s_waitcnt lgkmcnt(4)
	v_mfma_f32_32x32x16_bf16 v[16:31], v[64:67], v[204:207], v[16:31]
	v_mfma_f32_32x32x16_bf16 v[16:31], v[68:71], v[208:211], v[16:31]
	s_waitcnt lgkmcnt(0)
	v_mfma_f32_32x32x16_bf16 v[16:31], v[72:75], v[212:215], v[16:31]
	s_waitcnt vmcnt(3)
	ds_write_b128 v195, v[138:141] offset:32768
	v_mfma_f32_32x32x16_bf16 v[16:31], v[76:79], v[216:219], v[16:31]
	v_cmp_ge_f32_e32 vcc, s45, v252
	s_cmp_eq_u64 vcc, exec
	v_mov_b32_e32 v203, 1.0
	s_cbranch_scc0 .LBB0_231

; #define SBAR() __builtin_amdgcn_sched_barrier(0)
; #define KWRITE(b, src0, src1) do { if constexpr (ND0 == 4) { *(bf16x8*)(K_lds + (b) * SHM_K + KSWZ(kr, kcb)) = src0; } \
;     else { int kc = sc * 2; *(bf16x8*)(K_lds + (b) * SHM_K + KSWZ(sr, kc)) = src0; *(bf16x8*)(K_lds + (b) * SHM_K + KSWZ(32 + sr, kc)) = src1; } } while (0)
; #define SLOAD_A(k0) do { vs0a = *reinterpret_cast<const bf16x8*>(&Vh[(long)((k0) + sr) * LDK + sc]); vs1a = *reinterpret_cast<const bf16x8*>(&Vh[(long)((k0) + 32 + sr) * LDK + sc]); KLOAD(ks0a, ks1a, k0); } while (0)
; #define PSM(P0, P1, MN, AL) do { if constexpr (PRE) partialSM_pre(P0, P1, m_reg, AL, 11.541560327111707f); else partialSM(P0, P1, m_reg, MN, AL, C, thr_raw); } while (0)
; __device__ __forceinline__ void finishSM(f32x16& p0, f32x16& p1, float alpha, float& l_reg, bf16x8& pa0, bf16x8& pa1, bf16x8& pa2, bf16x8& pa3) {
; #pragma unroll
;   for (int r = 0; r < 16; ++r) p1[r] = __builtin_amdgcn_exp2f(p1[r]);
;   float ps = 0;
; #pragma unroll
;   for (int r = 0; r < 16; ++r) ps += p0[r];
; #pragma unroll
;   for (int r = 0; r < 16; ++r) ps += p1[r];
;   { auto rr = __builtin_amdgcn_permlane32_swap(__float_as_uint(ps), __float_as_uint(ps), false, false);
;     ps = __uint_as_float(rr[0]) + __uint_as_float(rr[1]); }
;   l_reg = l_reg * alpha + ps;
;     ...
;   PK4(p0, 0, pa0); PK4(p0, 8, pa1); PK4(p1, 0, pa2); PK4(p1, 8, pa3);
;     ...
; }
; template <int ND0>
; __device__ __forceinline__ void qkt(f32x16& p0, f32x16& p1, const char* Ks, const bf16x8* qr, int r32, int hi) {
;   p0 = f32x16{}; p1 = f32x16{};
; #pragma unroll
;   for (int d0 = 0; d0 < ND0; ++d0) { int cb = (d0 * 16 + hi * 8) * 2;
;     bf16x8 b0 = *reinterpret_cast<const bf16x8*>(Ks + KSWZ(r32, cb));
;     bf16x8 b1 = *reinterpret_cast<const bf16x8*>(Ks + KSWZ(32 + r32, cb));
;     p0 = __builtin_amdgcn_mfma_f32_32x32x16_bf16(b0, qr[d0], p0, 0, 0, 0);
;     p1 = __builtin_amdgcn_mfma_f32_32x32x16_bf16(b1, qr[d0], p1, 0, 0, 0); }
; }
; template <int ND0, int LDQ, int LDK, int LDO> ...
;     ...
;     SBAR(); qkt<ND0>(pA0, pA1, Kq0, qr, r32, hi);
;     finishSM(pB0, pB1, alB, l_reg, pa0, pa1, pa2, pa3); SBAR();
;     if (j + 3 < NT) SLOAD_A((j + 3) * KVBLK); SBAR();
;     pv_d0(o, vb0 + (int)SHM_V, pa0, pa1, pa2, pa3); KWRITE(1, ks0b, ks1b); PSM(pA0, pA1, mnA, alA);
.LBB0_220:
	ds_read_b128 v[222:225], v198 offset:32768
	ds_read_b128 v[244:247], v198 offset:40960
	ds_read_b128 v[130:133], v199 offset:32768
	ds_read_b128 v[134:137], v199 offset:40960
	ds_read_b128 v[138:141], v196 offset:32768
	v_exp_f32_e32 v226, v84
	v_exp_f32_e32 v227, v85
	s_waitcnt lgkmcnt(5)
	v_mfma_f32_32x32x16_bf16 v[96:111], v[64:67], v[126:129], 0
	v_exp_f32_e32 v234, v86
	v_exp_f32_e32 v235, v87
	v_exp_f32_e32 v236, v88
	v_exp_f32_e32 v237, v89
	v_exp_f32_e32 v238, v90
	v_exp_f32_e32 v239, v91
	v_exp_f32_e32 v240, v92
	v_mfma_f32_32x32x16_bf16 v[64:79], v[68:71], v[126:129], 0
	v_exp_f32_e32 v241, v93
	v_exp_f32_e32 v95, v95
	s_waitcnt lgkmcnt(3)
	v_mfma_f32_32x32x16_bf16 v[96:111], v[222:225], v[122:125], v[96:111]
	v_mfma_f32_32x32x16_bf16 v[64:79], v[244:247], v[122:125], v[64:79]
	ds_read_b128 v[244:247], v196 offset:40960
	s_waitcnt lgkmcnt(2)
	v_mfma_f32_32x32x16_bf16 v[96:111], v[130:133], v[118:121], v[96:111]
	v_mfma_f32_32x32x16_bf16 v[64:79], v[134:137], v[118:121], v[64:79]
	s_waitcnt lgkmcnt(0)
	v_mfma_f32_32x32x16_bf16 v[96:111], v[138:141], v[114:117], v[96:111]
	v_exp_f32_e32 v222, v80
	v_add_f32_e32 v80, 0, v219
	v_add_f32_e32 v80, v221, v80
	v_add_f32_e32 v80, v217, v80
	v_add_f32_e32 v80, v220, v80
	v_add_f32_e32 v80, v215, v80
	v_add_f32_e32 v80, v218, v80
	v_add_f32_e32 v80, v214, v80
	v_add_f32_e32 v80, v216, v80
	v_add_f32_e32 v80, v211, v80
	v_add_f32_e32 v80, v213, v80
	v_add_f32_e32 v80, v209, v80
	v_add_f32_e32 v80, v212, v80
	v_add_f32_e32 v80, v207, v80
	v_exp_f32_e32 v223, v81
	v_add_f32_e32 v80, v210, v80
	v_exp_f32_e32 v224, v82
	v_add_f32_e32 v80, v206, v80
	v_exp_f32_e32 v225, v83
	v_add_f32_e32 v80, v208, v80
	v_add_f32_e32 v80, v222, v80
	v_add_f32_e32 v80, v223, v80
	v_add_f32_e32 v80, v224, v80
	v_add_f32_e32 v80, v225, v80
	v_add_f32_e32 v80, v226, v80
	v_add_f32_e32 v80, v227, v80
	v_add_f32_e32 v80, v234, v80
	v_add_f32_e32 v80, v235, v80
	v_add_f32_e32 v80, v236, v80
	v_add_f32_e32 v80, v237, v80
	v_mfma_f32_32x32x16_bf16 v[64:79], v[244:247], v[114:117], v[64:79]
	v_exp_f32_e32 v244, v94
	v_add_f32_e32 v80, v238, v80
	v_add_f32_e32 v80, v239, v80
	v_add_f32_e32 v80, v240, v80
	v_add_f32_e32 v80, v241, v80
	v_add_f32_e32 v80, v244, v80
	v_add_f32_e32 v204, v95, v80
	v_mov_b32_e32 v205, v204
	v_cvt_pk_bf16_f32 v80, v219, v221
	v_cvt_pk_bf16_f32 v81, v217, v220
	v_cvt_pk_bf16_f32 v82, v215, v218
	v_cvt_pk_bf16_f32 v83, v214, v216
	v_cvt_pk_bf16_f32 v84, v211, v213
	v_cvt_pk_bf16_f32 v85, v209, v212
	v_cvt_pk_bf16_f32 v86, v207, v210
	v_cvt_pk_bf16_f32 v87, v206, v208
	v_cvt_pk_bf16_f32 v88, v222, v223
	v_cvt_pk_bf16_f32 v89, v224, v225
	v_cvt_pk_bf16_f32 v90, v226, v227
	v_cvt_pk_bf16_f32 v91, v234, v235
	v_cvt_pk_bf16_f32 v92, v236, v237
	v_cvt_pk_bf16_f32 v93, v238, v239
	v_cvt_pk_bf16_f32 v94, v240, v241
	v_cvt_pk_bf16_f32 v95, v244, v95
	v_permlane32_swap_b32_e32 v204, v205
	v_permlane32_swap_b32_e32 v80, v82
	v_permlane32_swap_b32_e32 v81, v83
	v_permlane32_swap_b32_e32 v84, v86
	v_permlane32_swap_b32_e32 v85, v87
	v_permlane32_swap_b32_e32 v88, v90
	v_permlane32_swap_b32_e32 v89, v91
	v_permlane32_swap_b32_e32 v92, v94
	v_permlane32_swap_b32_e32 v93, v95
	s_cmp_ge_u32 s40, s39
	s_cselect_b64 s[18:19], -1, 0
	s_and_b64 vcc, exec, s[18:19]
	s_cbranch_vccnz .Ldiff_pf_skip
	global_load_dwordx4 v[130:133], v[172:173], off
	v_lshl_add_u64 v[174:175], v[172:173], 0, s[34:35]
	global_load_dwordx4 v[134:137], v[174:175], off
	global_load_dwordx4 v[138:141], v[170:171], off offset:2048
	v_lshl_add_u64 v[172:173], v[172:173], 0, s[46:47]
	v_lshl_add_u64 v[170:171], v[170:171], 0, s[46:47]

; __device__ __forceinline__ void partialSM_pre(f32x16& p0, f32x16& p1, float& m_ref, float& alpha, const float thr2) {
;     ...
;   float pmax = p0[0];
; #pragma unroll
;   for (int r = 1; r < 16; ++r) pmax = fmaxf(pmax, p0[r]);
; #pragma unroll
;   for (int r = 0; r < 16; ++r) pmax = fmaxf(pmax, p1[r]);
;   { auto rr = __builtin_amdgcn_permlane32_swap(__float_as_uint(pmax), __float_as_uint(pmax), false, false);
;     pmax = fmaxf(__uint_as_float(rr[0]), __uint_as_float(rr[1])); }
;   if (__builtin_expect(__all(pmax <= thr2), 1)) { alpha = 1.f; }
.LBB0_223:
	v_max_f32_e32 v252, v96, v97
	v_max3_f32 v252, v252, v98, v99
	v_max3_f32 v252, v252, v100, v101
	v_max3_f32 v252, v252, v102, v103
	v_max3_f32 v252, v252, v104, v105
	v_max3_f32 v252, v252, v106, v107
	v_max3_f32 v252, v252, v108, v109
	v_max3_f32 v252, v252, v110, v111
	v_max3_f32 v252, v252, v64, v65
	v_max3_f32 v252, v252, v66, v67
	v_max3_f32 v252, v252, v68, v69
	v_max3_f32 v252, v252, v70, v71
	v_max3_f32 v252, v252, v72, v73
	v_max3_f32 v252, v252, v74, v75
	v_max3_f32 v252, v252, v76, v77
	v_max3_f32 v252, v252, v78, v79
	v_mov_b32_e32 v253, v252
	s_nop 1
	v_permlane32_swap_b32_e32 v252, v253
	v_max_f32_e32 v252, v252, v253
	s_waitcnt lgkmcnt(4)
	v_mfma_f32_32x32x16_bf16 v[0:15], v[80:83], v[174:177], v[0:15]
	ds_read_b64_tr_b16 v[174:175], v190 offset:0x200
	ds_read_b64_tr_b16 v[176:177], v190 offset:0xa00
	v_mfma_f32_32x32x16_bf16 v[0:15], v[84:87], v[206:209], v[0:15]
	ds_read_b64_tr_b16 v[206:207], v190 offset:0x1200
	ds_read_b64_tr_b16 v[208:209], v190 offset:0x1a00
	s_waitcnt lgkmcnt(4)
	v_mfma_f32_32x32x16_bf16 v[0:15], v[88:91], v[210:213], v[0:15]
	ds_read_b64_tr_b16 v[210:211], v190 offset:0x2200
	ds_read_b64_tr_b16 v[212:213], v190 offset:0x2a00
	v_mfma_f32_32x32x16_bf16 v[0:15], v[92:95], v[214:217], v[0:15]
	ds_read_b64_tr_b16 v[214:215], v190 offset:0x3200
	ds_read_b64_tr_b16 v[216:217], v190 offset:0x3a00
	s_waitcnt lgkmcnt(4)
	v_mfma_f32_32x32x16_bf16 v[48:63], v[80:83], v[174:177], v[48:63]
	ds_read_b64_tr_b16 v[174:175], v190 offset:0x400
	ds_read_b64_tr_b16 v[176:177], v190 offset:0xc00
	v_mfma_f32_32x32x16_bf16 v[48:63], v[84:87], v[206:209], v[48:63]
	ds_read_b64_tr_b16 v[206:207], v190 offset:0x1400
	ds_read_b64_tr_b16 v[208:209], v190 offset:0x1c00
	s_waitcnt lgkmcnt(4)
	v_mfma_f32_32x32x16_bf16 v[48:63], v[88:91], v[210:213], v[48:63]
	ds_read_b64_tr_b16 v[210:211], v190 offset:0x2400
	ds_read_b64_tr_b16 v[212:213], v190 offset:0x2c00
	v_mfma_f32_32x32x16_bf16 v[48:63], v[92:95], v[214:217], v[48:63]
	ds_read_b64_tr_b16 v[214:215], v190 offset:0x3400
	ds_read_b64_tr_b16 v[216:217], v190 offset:0x3c00
	s_waitcnt lgkmcnt(4)
	v_mfma_f32_32x32x16_bf16 v[32:47], v[80:83], v[174:177], v[32:47]
	ds_read_b64_tr_b16 v[174:175], v190 offset:0x600
	ds_read_b64_tr_b16 v[176:177], v190 offset:0xe00
	v_mfma_f32_32x32x16_bf16 v[32:47], v[84:87], v[206:209], v[32:47]
	ds_read_b64_tr_b16 v[206:207], v190 offset:0x1600
	ds_read_b64_tr_b16 v[208:209], v190 offset:0x1e00
	s_waitcnt lgkmcnt(4)
	v_mfma_f32_32x32x16_bf16 v[32:47], v[88:91], v[210:213], v[32:47]
	ds_read_b64_tr_b16 v[210:211], v190 offset:0x2600
	ds_read_b64_tr_b16 v[212:213], v190 offset:0x2e00
	v_mfma_f32_32x32x16_bf16 v[32:47], v[92:95], v[214:217], v[32:47]
	ds_read_b64_tr_b16 v[214:215], v190 offset:0x3600
	ds_read_b64_tr_b16 v[216:217], v190 offset:0x3e00
	s_waitcnt lgkmcnt(4)
	v_mfma_f32_32x32x16_bf16 v[16:31], v[80:83], v[174:177], v[16:31]
	v_mfma_f32_32x32x16_bf16 v[16:31], v[84:87], v[206:209], v[16:31]
	s_waitcnt lgkmcnt(0)
	v_mfma_f32_32x32x16_bf16 v[16:31], v[88:91], v[210:213], v[16:31]
	s_waitcnt vmcnt(3)
	ds_write_b128 v195, v[150:153] offset:49152
	v_mfma_f32_32x32x16_bf16 v[16:31], v[92:95], v[214:217], v[16:31]
	v_cmp_ge_f32_e32 vcc, s45, v252
	s_cmp_eq_u64 vcc, exec
	v_mov_b32_e32 v150, 1.0
	s_cbranch_scc0 .LBB0_233

; #define SBAR() __builtin_amdgcn_sched_barrier(0)
; #define KWRITE(b, src0, src1) do { if constexpr (ND0 == 4) { *(bf16x8*)(K_lds + (b) * SHM_K + KSWZ(kr, kcb)) = src0; } \
;     else { int kc = sc * 2; *(bf16x8*)(K_lds + (b) * SHM_K + KSWZ(sr, kc)) = src0; *(bf16x8*)(K_lds + (b) * SHM_K + KSWZ(32 + sr, kc)) = src1; } } while (0)
; #define SLOAD_A(k0) do { vs0a = *reinterpret_cast<const bf16x8*>(&Vh[(long)((k0) + sr) * LDK + sc]); vs1a = *reinterpret_cast<const bf16x8*>(&Vh[(long)((k0) + 32 + sr) * LDK + sc]); KLOAD(ks0a, ks1a, k0); } while (0)
; #define SLOAD_B(k0) do { vs0b = *reinterpret_cast<const bf16x8*>(&Vh[(long)((k0) + sr) * LDK + sc]); vs1b = *reinterpret_cast<const bf16x8*>(&Vh[(long)((k0) + 32 + sr) * LDK + sc]); KLOAD(ks0b, ks1b, k0); } while (0)
; #define VWRITE_A(b) do { *(bf16x8*)(V_lds + (b) * SHM_V + vst0) = vs0a; *(bf16x8*)(V_lds + (b) * SHM_V + vst1) = vs1a; } while (0)
; #define VWRITE_B(b) do { *(bf16x8*)(V_lds + (b) * SHM_V + vst0) = vs0b; *(bf16x8*)(V_lds + (b) * SHM_V + vst1) = vs1b; } while (0)
; #define SWAIT() do { if constexpr (ND0 == 4) asm volatile("s_waitcnt vmcnt(3)" ::: "memory"); else asm volatile("s_waitcnt vmcnt(4)" ::: "memory"); } while (0)
; __device__ __forceinline__ void partialSM_pre(f32x16& p0, f32x16& p1, float& m_ref, float& alpha, const float thr2) {
;     ...
;     for (int r = 0; r < 16; ++r) { p0[r] -= dl; p1[r] -= dl; } }
; #pragma unroll
;   for (int r = 0; r < 16; ++r) p0[r] = __builtin_amdgcn_exp2f(p0[r]);
; }
; template <int ND0, int LDQ, int LDK, int LDO> ...
;     ...
;   for (int j = 1; j + 1 < NT; j += 2) {
;     SBAR(); qkt<ND0>(pB0, pB1, Kq1, qr, r32, hi);
;     finishSM(pA0, pA1, alA, l_reg, pa0, pa1, pa2, pa3); SBAR();
;     SLOAD_B((j + 2) * KVBLK); SBAR();
;     pv_d0(o, vb0, pa0, pa1, pa2, pa3); KWRITE(0, ks0a, ks1a); PSM(pB0, pB1, mnB, alB);
;     __syncthreads(); SWAIT(); VWRITE_A(0);
;     RESC(alB); __syncthreads();
;     SBAR(); qkt<ND0>(pA0, pA1, Kq0, qr, r32, hi);
;     finishSM(pB0, pB1, alB, l_reg, pa0, pa1, pa2, pa3); SBAR();
;     if (j + 3 < NT) SLOAD_A((j + 3) * KVBLK); SBAR();
;     pv_d0(o, vb0 + (int)SHM_V, pa0, pa1, pa2, pa3); KWRITE(1, ks0b, ks1b); PSM(pA0, pA1, mnA, alA);
;     __syncthreads(); SWAIT(); VWRITE_B(1);
;     RESC(alA); __syncthreads();
;   }
.LBB0_228:
	v_exp_f32_e32 v147, v104
	v_exp_f32_e32 v149, v105
	v_exp_f32_e32 v145, v106
	v_exp_f32_e32 v148, v107
	v_exp_f32_e32 v143, v108
	v_exp_f32_e32 v146, v109
	v_exp_f32_e32 v142, v110
	v_exp_f32_e32 v144, v111
	s_add_i32 s40, s40, 2
	s_and_b64 vcc, exec, s[18:19]
	s_cbranch_vccnz .LBB0_234
	v_mov_b32_e32 v200, v150
	s_branch .LBB0_214
